# early seam-1 + all sample-group HGRN2 units on computing workgroups (HS_SPLIT 0)
# baseline (speedup 1.0000x reference)
.LBB0_864:
	s_or_b64 exec, exec, s[0:1]
	s_add_i32 s0, 0, 0x20008
	v_mov_b32_e32 v1, s0
	s_waitcnt lgkmcnt(0)
	s_barrier
	ds_read_b64 v[4:5], v1
	s_mov_b32 s9, 0
	s_waitcnt lgkmcnt(0)
	v_readfirstlane_b32 s0, v4
	s_cmpk_gt_i32 s0, 0x1ff
	v_readfirstlane_b32 s8, v5
	s_cbranch_scc1 .LBB0_877
	s_add_i32 s10, s0, 0
	s_and_b32 s4, s10, -4
	s_ashr_i32 s11, s10, 31
	s_ashr_i32 s5, s4, 31
	s_lshl_b64 s[12:13], s[10:11], 16
	s_add_u32 s12, s66, s12
	s_addc_u32 s13, s67, s13
	v_ashrrev_i32_e32 v66, 7, v2
	s_add_u32 s14, s4, 0x4100
	s_addc_u32 s15, s5, 0
	v_ashrrev_i32_e32 v67, 31, v66
	v_lshl_add_u64 v[4:5], s[14:15], 0, v[66:67]
	s_lshl_b32 s0, s0, 7
	v_lshlrev_b64 v[4:5], 9, v[4:5]
	s_and_b32 s0, s0, 0x180
	v_or_b32_e32 v3, s0, v4
	s_lshl_b32 s0, s0, 1
	v_and_b32_e32 v1, 31, v2
	v_mov_b32_e32 v69, 0
	s_add_u32 s0, s86, s0
	v_or_b32_e32 v4, v3, v83
	s_addc_u32 s1, s87, 0
	v_lshlrev_b32_e32 v12, 3, v1
	v_mov_b32_e32 v13, v69
	v_lshlrev_b64 v[4:5], 1, v[4:5]
	v_lshl_add_u64 v[14:15], s[0:1], 0, v[12:13]
	s_lshl_b64 s[0:1], s[14:15], 10
	v_lshl_add_u64 v[8:9], s[84:85], 0, v[4:5]
	v_lshl_add_u64 v[10:11], s[52:53], 0, v[4:5]
	v_lshl_add_u64 v[16:17], v[14:15], 0, s[0:1]
	v_lshl_add_u64 v[6:7], s[82:83], 0, v[4:5]
	global_load_dwordx2 v[94:95], v[16:17], off
	global_load_ushort v3, v[10:11], off
	s_nop 0
	global_load_ushort v10, v[6:7], off
	s_nop 0
	global_load_ushort v8, v[8:9], off
	v_lshl_add_u64 v[4:5], s[70:71], 0, v[4:5]
	v_ashrrev_i32_e32 v11, 5, v2
	global_load_ushort v9, v[4:5], off
	v_lshlrev_b32_e32 v4, 3, v11
	v_ashrrev_i32_e32 v5, 31, v4
	v_lshlrev_b64 v[4:5], 9, v[4:5]
	v_lshl_add_u64 v[6:7], s[12:13], 0, v[4:5]
	v_lshlrev_b32_e32 v68, 4, v1
	v_lshl_add_u64 v[6:7], v[6:7], 0, v[68:69]
	global_load_dwordx4 v[62:65], v[6:7], off
	global_load_dwordx4 v[58:61], v[6:7], off offset:512
	global_load_dwordx4 v[54:57], v[6:7], off offset:1024
	global_load_dwordx4 v[50:53], v[6:7], off offset:1536
	global_load_dwordx4 v[46:49], v[6:7], off offset:2048
	global_load_dwordx4 v[42:45], v[6:7], off offset:2560
	global_load_dwordx4 v[38:41], v[6:7], off offset:3072
	global_load_dwordx4 v[34:37], v[6:7], off offset:3584
	s_lshl_b64 s[0:1], s[4:5], 10
	v_lshl_add_u64 v[6:7], v[14:15], 0, s[0:1]
	s_mov_b32 s0, 0x1040000
	v_add_co_u32_e32 v6, vcc, s0, v6
	v_and_b32_e32 v1, 64, v182
	s_nop 0
	v_addc_co_u32_e32 v7, vcc, 0, v7, vcc
	global_load_dwordx2 v[100:101], v[6:7], off offset:1024
	global_load_dwordx2 v[98:99], v[6:7], off offset:2048
	global_load_dwordx2 v[96:97], v[6:7], off offset:3072
	v_xor_b32_e32 v7, 1, v182
	s_waitcnt vmcnt(20)
	v_add_u32_e32 v19, 64, v1
	v_xor_b32_e32 v14, 2, v182
	v_cmp_lt_i32_e32 vcc, v7, v19
	v_lshl_add_u32 v6, v83, 2, 0
	s_movk_i32 s0, 0x600
	v_xor_b32_e32 v15, 4, v182
	v_cndmask_b32_e32 v1, v182, v7, vcc
	v_cmp_lt_i32_e32 vcc, v14, v19
	v_xor_b32_e32 v16, 8, v182
	v_mad_u64_u32 v[70:71], s[0:1], v66, s0, v[6:7]
	v_cndmask_b32_e32 v7, v182, v14, vcc
	v_cmp_lt_i32_e32 vcc, v15, v19
	v_xor_b32_e32 v17, 16, v182
	v_lshl_add_u64 v[72:73], s[86:87], 0, v[12:13]
	v_cndmask_b32_e32 v12, v182, v15, vcc
	v_cmp_lt_i32_e32 vcc, v16, v19
	v_lshl_add_u32 v108, v66, 3, 0
	v_readlane_b32 s16, v254, 4
	v_cndmask_b32_e32 v13, v182, v16, vcc
	v_cmp_lt_i32_e32 vcc, v17, v19
	v_readlane_b32 s30, v254, 18
	v_readlane_b32 s31, v254, 19
	v_cndmask_b32_e32 v14, v182, v17, vcc
	v_lshl_add_u32 v11, v11, 9, 0
	v_lshlrev_b32_e32 v18, 13, v66
	v_add_u32_e32 v74, 0x4100, v66
	s_add_u32 s12, s72, 0x10000400
	v_readlane_b32 s18, v254, 6
	v_readlane_b32 s19, v254, 7
	v_readlane_b32 s20, v254, 8
	s_mov_b64 s[4:5], 0x8524400
	v_lshlrev_b32_e32 v71, 2, v1
	v_lshlrev_b32_e32 v103, 2, v7
	v_lshlrev_b32_e32 v104, 2, v12
	v_lshlrev_b32_e32 v105, 2, v13
	v_lshlrev_b32_e32 v106, 2, v14
	v_ashrrev_i32_e32 v75, 31, v74
	s_addc_u32 s13, s73, 0
	v_add_u32_e32 v111, v11, v68
	v_add_u32_e32 v112, v6, v18
	v_mov_b32_e32 v113, 0x358637bd
	s_mov_b32 s18, 0xf800000
	v_mov_b32_e32 v114, 0x260
	s_movk_i32 s19, 0x7fff
	s_mov_b32 s20, 0
	v_mov_b32_e32 v115, 0
	v_readlane_b32 s17, v254, 5
	v_readlane_b32 s21, v254, 9
	v_readlane_b32 s22, v254, 10
	v_readlane_b32 s23, v254, 11
	v_readlane_b32 s24, v254, 12
	v_readlane_b32 s25, v254, 13
	v_readlane_b32 s26, v254, 14
	v_readlane_b32 s27, v254, 15
	v_readlane_b32 s28, v254, 16
	v_readlane_b32 s29, v254, 17
	s_waitcnt vmcnt(14)
	v_lshlrev_b32_e32 v81, 16, v3
	v_xor_b32_e32 v3, 32, v182
	v_cmp_lt_i32_e32 vcc, v3, v19
	s_waitcnt vmcnt(13)
	v_lshlrev_b32_e32 v1, 16, v10
	s_waitcnt vmcnt(12)
	v_lshlrev_b32_e32 v82, 16, v8
	v_cndmask_b32_e32 v3, v182, v3, vcc
	v_lshlrev_b32_e32 v107, 2, v3
	v_and_b32_e32 v3, 63, v2
	v_cmp_eq_u32_e64 s[0:1], 0, v3
	v_lshrrev_b32_e32 v3, 4, v2
	v_and_b32_e32 v3, 4, v3
	v_and_b32_e32 v2, 0xffffffe0, v2
	v_add_u32_e32 v109, v108, v3
	v_add_u32_e32 v110, 0, v2
	v_lshl_add_u64 v[2:3], s[66:67], 0, v[4:5]
	v_lshl_add_u64 v[76:77], v[2:3], 0, v[68:69]
	v_lshl_add_u64 v[2:3], s[30:31], 0, v[4:5]
	v_lshl_add_u64 v[2:3], v[2:3], 0, v[68:69]
	s_waitcnt vmcnt(11)
	v_lshlrev_b32_e32 v80, 16, v9
	v_lshl_add_u64 v[78:79], v[2:3], 0, s[4:5]
	s_branch .LBB0_867

.LBB0_871:
	s_or_b64 exec, exec, s[4:5]
	v_mul_f32_e32 v2, 0x3fb8aa3b, v1
	v_exp_f32_e32 v2, v2
	s_add_i32 s14, s8, 0
	s_cmpk_gt_i32 s8, 0x1ff
	s_cselect_b64 s[16:17], -1, 0
	ds_write2st64_b32 v70, v2, v82 offset1:2
	s_waitcnt vmcnt(10)
	v_mov_b64_e32 v[2:3], v[62:63]
	s_waitcnt vmcnt(9)
	v_mov_b64_e32 v[6:7], v[58:59]
	s_waitcnt vmcnt(8)
	v_mov_b64_e32 v[10:11], v[54:55]
	s_waitcnt vmcnt(7)
	v_mov_b64_e32 v[14:15], v[50:51]
	s_waitcnt vmcnt(6)
	v_mov_b64_e32 v[18:19], v[46:47]
	s_waitcnt vmcnt(5)
	v_mov_b64_e32 v[22:23], v[42:43]
	s_waitcnt vmcnt(4)
	v_mov_b64_e32 v[26:27], v[38:39]
	s_waitcnt vmcnt(3)
	v_mov_b64_e32 v[30:31], v[34:35]
	s_and_b64 vcc, exec, s[16:17]
	v_mov_b64_e32 v[84:85], v[94:95]
	s_waitcnt vmcnt(2)
	v_mov_b64_e32 v[86:87], v[100:101]
	s_waitcnt vmcnt(1)
	v_mov_b64_e32 v[88:89], v[98:99]
	s_waitcnt vmcnt(0)
	v_mov_b64_e32 v[92:93], v[96:97]
	v_mov_b64_e32 v[4:5], v[64:65]
	v_mov_b64_e32 v[8:9], v[60:61]
	v_mov_b64_e32 v[12:13], v[56:57]
	v_mov_b64_e32 v[16:17], v[52:53]
	v_mov_b64_e32 v[20:21], v[48:49]
	v_mov_b64_e32 v[24:25], v[44:45]
	v_mov_b64_e32 v[28:29], v[40:41]
	v_mov_b64_e32 v[32:33], v[36:37]
	v_mov_b64_e32 v[90:91], v[80:81]
	ds_write_b32 v70, v81 offset:1024
	s_cbranch_vccnz .LBB0_873
	s_and_b32 s4, s14, -4
	s_ashr_i32 s15, s14, 31
	s_ashr_i32 s5, s4, 31
	s_lshl_b64 s[22:23], s[14:15], 16
	v_lshl_add_u64 v[30:31], v[76:77], 0, s[22:23]
	s_add_u32 s22, s4, 0x4100
	s_addc_u32 s23, s5, 0
	v_lshl_add_u64 v[84:85], s[22:23], 0, v[66:67]
	s_lshl_b32 s8, s8, 7
	v_lshlrev_b64 v[84:85], 9, v[84:85]
	s_and_b32 s8, s8, 0x180
	v_or_b32_e32 v1, s8, v84
	v_or_b32_e32 v84, v1, v83
	s_lshl_b32 s8, s8, 1
	global_load_dwordx4 v[2:5], v[30:31], off
	global_load_dwordx4 v[6:9], v[30:31], off offset:512
	global_load_dwordx4 v[10:13], v[30:31], off offset:1024
	global_load_dwordx4 v[14:17], v[30:31], off offset:1536
	global_load_dwordx4 v[18:21], v[30:31], off offset:2048
	global_load_dwordx4 v[22:25], v[30:31], off offset:2560
	global_load_dwordx4 v[26:29], v[30:31], off offset:3072
	s_nop 0
	global_load_dwordx4 v[30:33], v[30:31], off offset:3584
	v_lshlrev_b64 v[84:85], 1, v[84:85]
	v_lshl_add_u64 v[92:93], v[72:73], 0, s[8:9]
	s_lshl_b64 s[22:23], s[22:23], 10
	v_lshl_add_u64 v[86:87], s[82:83], 0, v[84:85]
	v_lshl_add_u64 v[88:89], s[84:85], 0, v[84:85]
	v_lshl_add_u64 v[90:91], s[52:53], 0, v[84:85]
	v_lshl_add_u64 v[84:85], s[70:71], 0, v[84:85]
	v_lshl_add_u64 v[116:117], v[92:93], 0, s[22:23]
	s_lshl_b64 s[4:5], s[4:5], 10
	global_load_ushort v68, v[88:89], off
	global_load_ushort v81, v[84:85], off
	s_nop 0
	global_load_dwordx2 v[84:85], v[116:117], off
	s_nop 0
	global_load_ushort v116, v[90:91], off
	global_load_ushort v1, v[86:87], off
	v_lshl_add_u64 v[86:87], v[92:93], 0, s[4:5]
	v_add_co_u32_e32 v90, vcc, 0x1040000, v86
	s_waitcnt vmcnt(4)
	v_lshlrev_b32_e32 v82, 16, v68
	v_addc_co_u32_e32 v91, vcc, 0, v87, vcc
	global_load_dwordx2 v[86:87], v[90:91], off offset:1024
	global_load_dwordx2 v[88:89], v[90:91], off offset:2048
	global_load_dwordx2 v[92:93], v[90:91], off offset:3072
	s_waitcnt vmcnt(3)
	v_lshlrev_b32_e32 v1, 16, v1
	v_lshlrev_b32_e32 v91, 16, v116
	v_lshlrev_b32_e32 v90, 16, v81

.LBB0_1081:
	s_or_b64 exec, exec, s[0:1]
	v_mov_b32_e32 v2, v0
	s_cmp_eq_u32 s8, s8
	s_barrier
	s_cbranch_scc1 .LBB0_1088
	s_add_u32 s4, s72, 0x7400000
	s_addc_u32 s5, s73, 0
	s_add_u32 s6, s72, 0x8500000
	s_addc_u32 s7, s73, 0
	s_add_u32 s10, s72, 0xa700000
	s_addc_u32 s11, s73, 0
	s_add_u32 s12, s72, 0xb800000
	s_addc_u32 s13, s73, 0
	s_add_u32 s0, s72, 0x9600000
	s_mov_b32 s9, 0
	s_addc_u32 s1, s73, 0
	v_ashrrev_i32_e32 v70, 7, v2
	s_and_b32 s16, s8, 0x1fc
	s_add_i32 s2, s16, 0x4100
	s_mov_b32 s3, s9
	v_ashrrev_i32_e32 v71, 31, v70
	s_lshl_b32 s8, s8, 7
	v_lshl_add_u64 v[6:7], v[70:71], 0, s[2:3]
	v_and_b32_e32 v66, 0x7f, v2
	v_lshlrev_b64 v[6:7], 9, v[6:7]
	s_and_b32 s3, s8, 0x180
	v_ashrrev_i32_e32 v1, 5, v2
	v_or3_b32 v6, v6, s3, v66
	s_lshl_b32 s3, s3, 1
	v_mov_b32_e32 v69, 0
	v_and_b32_e32 v3, 31, v2
	v_lshlrev_b32_e32 v72, 3, v1
	s_add_u32 s14, s0, s3
	v_ashrrev_i32_e32 v73, 31, v72
	s_addc_u32 s15, s1, 0
	v_lshlrev_b32_e32 v14, 3, v3
	v_mov_b32_e32 v15, v69
	v_lshl_add_u64 v[4:5], v[72:73], 0, s[8:9]
	v_lshlrev_b64 v[6:7], 1, v[6:7]
	v_lshl_add_u64 v[16:17], s[14:15], 0, v[14:15]
	s_lshl_b32 s8, s2, 10
	v_lshl_add_u64 v[8:9], s[12:13], 0, v[6:7]
	v_lshl_add_u64 v[10:11], s[6:7], 0, v[6:7]
	v_lshl_add_u64 v[12:13], s[4:5], 0, v[6:7]
	v_lshl_add_u64 v[18:19], v[16:17], 0, s[8:9]
	v_lshl_add_u64 v[6:7], s[10:11], 0, v[6:7]
	global_load_dwordx2 v[96:97], v[18:19], off
	global_load_ushort v20, v[12:13], off
	global_load_ushort v21, v[8:9], off
	global_load_ushort v22, v[10:11], off
	s_lshl_b32 s8, s16, 10
	global_load_ushort v8, v[6:7], off
	s_mov_b32 s2, 0x1040000
	v_lshl_add_u64 v[6:7], v[16:17], 0, s[8:9]
	v_lshlrev_b64 v[4:5], 9, v[4:5]
	v_add_co_u32_e32 v6, vcc, s2, v6
	v_lshlrev_b32_e32 v68, 4, v3
	v_lshl_add_u64 v[4:5], s[66:67], 0, v[4:5]
	v_addc_co_u32_e32 v7, vcc, 0, v7, vcc
	v_readlane_b32 s16, v254, 4
	v_lshl_add_u64 v[4:5], v[4:5], 0, v[68:69]
	global_load_dwordx2 v[102:103], v[6:7], off offset:1024
	global_load_dwordx2 v[100:101], v[6:7], off offset:2048
	global_load_dwordx2 v[98:99], v[6:7], off offset:3072
	global_load_dwordx4 v[62:65], v[4:5], off
	global_load_dwordx4 v[58:61], v[4:5], off offset:512
	global_load_dwordx4 v[54:57], v[4:5], off offset:1024
	global_load_dwordx4 v[50:53], v[4:5], off offset:1536
	global_load_dwordx4 v[46:49], v[4:5], off offset:2048
	global_load_dwordx4 v[42:45], v[4:5], off offset:2560
	global_load_dwordx4 v[38:41], v[4:5], off offset:3072
	global_load_dwordx4 v[34:37], v[4:5], off offset:3584
	v_readlane_b32 s22, v254, 10
	v_readlane_b32 s23, v254, 11
	v_lshlrev_b32_e32 v3, 2, v66
	s_mov_b64 s[14:15], s[22:23]
	global_load_dword v67, v3, s[14:15]
	v_mbcnt_hi_u32_b32 v5, -1, v232
	v_lshl_add_u32 v6, v1, 9, 0
	v_and_b32_e32 v1, 64, v5
	v_xor_b32_e32 v9, 1, v5
	v_add_u32_e32 v4, 0, v3
	v_add_u32_e32 v3, 64, v1
	v_xor_b32_e32 v10, 2, v5
	v_cmp_lt_i32_e32 vcc, v9, v3
	v_xor_b32_e32 v11, 4, v5
	v_xor_b32_e32 v12, 8, v5
	v_cndmask_b32_e32 v1, v5, v9, vcc
	v_cmp_lt_i32_e32 vcc, v10, v3
	v_readlane_b32 s30, v254, 18
	v_readlane_b32 s31, v254, 19
	v_cndmask_b32_e32 v9, v5, v10, vcc
	v_cmp_lt_i32_e32 vcc, v11, v3
	s_movk_i32 s2, 0x600
	v_lshl_add_u64 v[76:77], s[0:1], 0, v[14:15]
	v_cndmask_b32_e32 v10, v5, v11, vcc
	v_cmp_lt_i32_e32 vcc, v12, v3
	s_mov_b64 s[22:23], s[30:31]
	v_mad_u64_u32 v[74:75], s[2:3], v70, s2, v[4:5]
	v_lshl_add_u32 v108, v70, 3, 0
	v_lshlrev_b32_e32 v7, 13, v70
	s_add_u32 s14, s72, 0x10000400
	s_mov_b64 s[2:3], 0x8524400
	v_readlane_b32 s18, v254, 6
	v_readlane_b32 s19, v254, 7
	v_lshlrev_b32_e32 v75, 2, v1
	v_lshlrev_b32_e32 v85, 2, v9
	v_lshlrev_b32_e32 v104, 2, v10
	s_addc_u32 s15, s73, 0
	v_add_u32_e32 v111, v6, v68
	v_add_u32_e32 v112, v4, v7
	v_lshl_add_u64 v[78:79], s[66:67], 0, v[68:69]
	v_mov_b32_e32 v113, 0x358637bd
	s_mov_b32 s18, 0xf800000
	v_mov_b32_e32 v114, 0x260
	s_movk_i32 s19, 0x7fff
	v_readlane_b32 s17, v254, 5
	v_readlane_b32 s20, v254, 8
	v_readlane_b32 s21, v254, 9
	v_readlane_b32 s24, v254, 12
	v_readlane_b32 s25, v254, 13
	v_readlane_b32 s26, v254, 14
	v_readlane_b32 s27, v254, 15
	v_readlane_b32 s28, v254, 16
	v_readlane_b32 s29, v254, 17
	s_waitcnt vmcnt(16)
	v_mov_b64_e32 v[86:87], v[96:97]
	s_waitcnt vmcnt(15)
	v_lshlrev_b32_e32 v83, 16, v20
	s_waitcnt vmcnt(14)
	v_lshlrev_b32_e32 v1, 16, v21
	s_waitcnt vmcnt(13)
	v_lshlrev_b32_e32 v84, 16, v22
	s_waitcnt vmcnt(12)
	v_lshlrev_b32_e32 v82, 16, v8
	v_cndmask_b32_e32 v8, v5, v12, vcc
	v_lshlrev_b32_e32 v105, 2, v8
	v_xor_b32_e32 v8, 16, v5
	v_cmp_lt_i32_e32 vcc, v8, v3
	s_waitcnt vmcnt(11)
	v_mov_b64_e32 v[88:89], v[102:103]
	s_waitcnt vmcnt(10)
	v_mov_b64_e32 v[90:91], v[100:101]
	v_cndmask_b32_e32 v8, v5, v8, vcc
	v_lshlrev_b32_e32 v106, 2, v8
	v_xor_b32_e32 v8, 32, v5
	v_cmp_lt_i32_e32 vcc, v8, v3
	s_waitcnt vmcnt(6)
	v_mov_b64_e32 v[10:11], v[54:55]
	s_waitcnt vmcnt(5)
	v_mov_b64_e32 v[14:15], v[50:51]
	v_cndmask_b32_e32 v3, v5, v8, vcc
	v_lshlrev_b32_e32 v107, 2, v3
	v_and_b32_e32 v3, 63, v2
	v_cmp_eq_u32_e64 s[0:1], 0, v3
	v_lshrrev_b32_e32 v3, 4, v2
	v_and_b32_e32 v3, 4, v3
	v_and_b32_e32 v2, 0xffffffe0, v2
	v_add_u32_e32 v109, v108, v3
	v_add_u32_e32 v110, 0, v2
	v_lshl_add_u64 v[2:3], s[22:23], 0, v[68:69]
	v_lshl_add_u64 v[80:81], v[2:3], 0, s[2:3]
	s_lshl_b32 s2, s94, 7
	v_mov_b64_e32 v[2:3], v[62:63]
	v_mov_b64_e32 v[6:7], v[58:59]
	s_waitcnt vmcnt(4)
	v_mov_b64_e32 v[18:19], v[46:47]
	s_waitcnt vmcnt(3)
	v_mov_b64_e32 v[22:23], v[42:43]
	s_waitcnt vmcnt(2)
	v_mov_b64_e32 v[26:27], v[38:39]
	s_waitcnt vmcnt(1)
	v_mov_b64_e32 v[30:31], v[34:35]
	s_add_i32 s8, s2, 0xffffa000
	s_add_i32 s2, s94, 0xffffff00
	v_lshlrev_b32_e32 v68, 1, v66
	v_mov_b64_e32 v[92:93], v[98:99]
	v_mov_b64_e32 v[4:5], v[64:65]
	v_mov_b64_e32 v[8:9], v[60:61]
	v_mov_b64_e32 v[12:13], v[56:57]
	v_mov_b64_e32 v[16:17], v[52:53]
	v_mov_b64_e32 v[20:21], v[48:49]
	v_mov_b64_e32 v[24:25], v[44:45]
	v_mov_b64_e32 v[28:29], v[40:41]
	v_mov_b64_e32 v[32:33], v[36:37]
	v_mov_b64_e32 v[94:95], v[82:83]
	s_branch .LBB0_1084
